# A/B loop: next-item tile prefetch addressing precomputed once per phase (12 VGPRs), six masked loads via SGPR base + VGPR offset
# speedup vs baseline: 1.5602x; 1.0034x over previous
.LBB0_794:
	s_and_b64 vcc, exec, s[38:39]
	s_cbranch_vccnz .LBB0_846
	v_readlane_b32 s6, v242, 0
	v_readlane_b32 s5, v242, 40
	v_readlane_b32 s7, v242, 1
	s_mul_i32 s2, s5, 0x180
	s_mov_b32 s3, s7
	s_lshl_b32 s4, s5, 3
	s_lshl_b64 s[2:3], s[2:3], 2
	s_add_u32 s30, s78, s2
	s_addc_u32 s31, s79, s3
	s_add_u32 s40, s82, s2
	s_addc_u32 s41, s83, s3
	s_mul_i32 s6, s5, 0x480
	s_add_u32 s42, s80, s2
	s_addc_u32 s43, s81, s3
	s_lshl_b64 s[2:3], s[6:7], 2
	s_add_u32 s94, s84, s2
	s_addc_u32 s95, s85, s3
	s_mov_b32 s2, 0xaaaaaaab
	v_mul_hi_u32 v255, v0, s2
	v_lshrrev_b32_e32 v255, 5, v255
	v_mul_u32_u24_e32 v241, 48, v255
	v_sub_u32_e32 v241, v0, v241
	v_lshlrev_b32_e32 v241, 4, v241
	v_lshl_add_u32 v241, v255, 12, v241
	v_cmp_gt_u32_e32 vcc, 62, v255
	v_cndmask_b32_e32 v234, -1, v255, vcc
	v_add_u32_e32 v254, 0x200, v0
	v_mul_hi_u32 v255, v254, s2
	v_lshrrev_b32_e32 v255, 5, v255
	v_mul_u32_u24_e32 v245, 48, v255
	v_sub_u32_e32 v245, v254, v245
	v_lshlrev_b32_e32 v245, 4, v245
	v_lshl_add_u32 v245, v255, 12, v245
	v_cmp_gt_u32_e32 vcc, 62, v255
	v_cndmask_b32_e32 v235, -1, v255, vcc
	v_add_u32_e32 v254, 0x400, v0
	v_mul_hi_u32 v255, v254, s2
	v_lshrrev_b32_e32 v255, 5, v255
	v_mul_u32_u24_e32 v246, 48, v255
	v_sub_u32_e32 v246, v254, v246
	v_lshlrev_b32_e32 v246, 4, v246
	v_lshl_add_u32 v246, v255, 12, v246
	v_cmp_gt_u32_e32 vcc, 62, v255
	v_cndmask_b32_e32 v236, -1, v255, vcc
	v_add_u32_e32 v254, 0x600, v0
	v_mul_hi_u32 v255, v254, s2
	v_lshrrev_b32_e32 v255, 5, v255
	v_mul_u32_u24_e32 v247, 48, v255
	v_sub_u32_e32 v247, v254, v247
	v_lshlrev_b32_e32 v247, 4, v247
	v_lshl_add_u32 v247, v255, 12, v247
	v_cmp_gt_u32_e32 vcc, 62, v255
	v_cndmask_b32_e32 v237, -1, v255, vcc
	v_add_u32_e32 v254, 0x800, v0
	v_mul_hi_u32 v255, v254, s2
	v_lshrrev_b32_e32 v255, 5, v255
	v_mul_u32_u24_e32 v252, 48, v255
	v_sub_u32_e32 v252, v254, v252
	v_lshlrev_b32_e32 v252, 4, v252
	v_lshl_add_u32 v252, v255, 12, v252
	v_cmp_gt_u32_e32 vcc, 62, v255
	v_cndmask_b32_e32 v238, -1, v255, vcc
	v_add_u32_e32 v254, 0xa00, v0
	v_mul_hi_u32 v255, v254, s2
	v_lshrrev_b32_e32 v255, 5, v255
	v_mul_u32_u24_e32 v253, 48, v255
	v_sub_u32_e32 v253, v254, v253
	v_lshlrev_b32_e32 v253, 4, v253
	v_lshl_add_u32 v253, v255, 12, v253
	v_cmp_gt_u32_e32 vcc, 62, v255
	v_cndmask_b32_e32 v239, -1, v255, vcc
	s_mov_b32 s6, s24
	v_and_b32_e32 v240, 63, v0
	v_min_u32_e32 v240, 47, v240
	v_lshlrev_b32_e32 v240, 5, v240
	global_load_dwordx4 v[186:189], v240, s[30:31]
	global_load_dwordx4 v[190:193], v240, s[30:31] offset:16
	global_load_dwordx4 v[194:197], v240, s[40:41]
	global_load_dwordx4 v[198:201], v240, s[40:41] offset:16
	global_load_dwordx4 v[202:205], v240, s[42:43]
	global_load_dwordx4 v[206:209], v240, s[42:43] offset:16
	global_load_dwordx4 v[210:213], v240, s[94:95] offset:3072
	global_load_dwordx4 v[214:217], v240, s[94:95] offset:3088
	global_load_dwordx4 v[218:221], v240, s[94:95] offset:1536
	global_load_dwordx4 v[222:225], v240, s[94:95] offset:1552
	global_load_dwordx4 v[226:229], v240, s[94:95]
	global_load_dwordx4 v[230:233], v240, s[94:95] offset:16
	s_branch .LBB0_797

.LBB0_797:
	s_add_i32 s5, s6, s46
	v_mov_b32_e32 v26, v0
	s_cmpk_gt_i32 s5, 0x1ff
	s_cselect_b64 s[34:35], -1, 0
	s_cmpk_lt_i32 s5, 0x200
	v_lshl_add_u32 v26, v26, 4, 32
	s_cselect_b32 s2, s5, s6
	v_add_u32_e32 v27, 0xd800, v26
	s_waitcnt vmcnt(8)
	ds_write_b128 v26, v[2:5] offset:55296
	ds_write_b128 v26, v[6:9] offset:63488
	ds_write_b128 v27, v[10:13] offset:16384
	ds_write_b128 v27, v[14:17] offset:24576
	ds_write_b128 v27, v[18:21] offset:32768
	ds_write_b128 v27, v[22:25] offset:40960
	s_lshl_b32 s7, s2, 5
	s_waitcnt lgkmcnt(0)
	s_barrier
	s_and_b32 s12, s7, 0x7e0
	s_sub_i32 s10, s7, 30
	s_ashr_i32 s11, s10, 31
	s_lshl_b64 s[10:11], s[10:11], 12
	s_add_u32 s10, s60, s10
	s_addc_u32 s11, s61, s11
	s_cmp_eq_u32 s12, 0
	s_cselect_b32 s13, 30, 0
	v_cmp_le_i32_e32 vcc, s13, v234
	v_mov_b32_e32 v2, 0
	v_mov_b32_e32 v3, 0
	v_mov_b32_e32 v4, 0
	v_mov_b32_e32 v5, 0
	s_and_saveexec_b64 s[2:3], vcc
	global_load_dwordx4 v[2:5], v241, s[10:11]
	s_or_b64 exec, exec, s[2:3]
	v_cmp_le_i32_e32 vcc, s13, v235
	v_mov_b32_e32 v6, 0
	v_mov_b32_e32 v7, 0
	v_mov_b32_e32 v8, 0
	v_mov_b32_e32 v9, 0
	s_and_saveexec_b64 s[2:3], vcc
	global_load_dwordx4 v[6:9], v245, s[10:11]
	s_or_b64 exec, exec, s[2:3]
	v_cmp_le_i32_e32 vcc, s13, v236
	v_mov_b32_e32 v10, 0
	v_mov_b32_e32 v11, 0
	v_mov_b32_e32 v12, 0
	v_mov_b32_e32 v13, 0
	s_and_saveexec_b64 s[2:3], vcc
	global_load_dwordx4 v[10:13], v246, s[10:11]
	s_or_b64 exec, exec, s[2:3]
	v_cmp_le_i32_e32 vcc, s13, v237
	v_mov_b32_e32 v14, 0
	v_mov_b32_e32 v15, 0
	v_mov_b32_e32 v16, 0
	v_mov_b32_e32 v17, 0
	s_and_saveexec_b64 s[2:3], vcc
	global_load_dwordx4 v[14:17], v247, s[10:11]
	s_or_b64 exec, exec, s[2:3]
	v_cmp_le_i32_e32 vcc, s13, v238
	v_mov_b32_e32 v18, 0
	v_mov_b32_e32 v19, 0
	v_mov_b32_e32 v20, 0
	v_mov_b32_e32 v21, 0
	s_and_saveexec_b64 s[2:3], vcc
	global_load_dwordx4 v[18:21], v252, s[10:11]
	s_or_b64 exec, exec, s[2:3]
	v_cmp_le_i32_e32 vcc, s13, v239
	v_mov_b32_e32 v22, 0
	v_mov_b32_e32 v23, 0
	v_mov_b32_e32 v24, 0
	v_mov_b32_e32 v25, 0
	s_and_saveexec_b64 s[2:3], vcc
	global_load_dwordx4 v[22:25], v253, s[10:11]
	s_or_b64 exec, exec, s[2:3]
	v_mov_b32_e32 v26, v0
	s_lshl_b32 s2, s6, 5
	v_ashrrev_i32_e32 v152, 6, v26
	v_lshlrev_b32_e32 v150, 2, v152
	v_and_b32_e32 v27, 63, v26
	s_ashr_i32 s3, s2, 31
	v_ashrrev_i32_e32 v151, 31, v150
	v_cmp_gt_u32_e64 s[38:39], 48, v27
	v_lshl_add_u64 v[148:149], v[150:151], 0, s[2:3]
	s_movk_i32 s3, 0x1000
	v_cndmask_b32_e64 v42, 47, v27, s[38:39]
	v_lshlrev_b64 v[26:27], 12, v[148:149]
	v_lshl_add_u64 v[82:83], s[60:61], 0, v[26:27]
	v_lshlrev_b32_e32 v154, 4, v42
	v_lshl_add_u64 v[56:57], v[82:83], 0, v[154:155]
	v_add_co_u32_e32 v26, vcc, s3, v56
	global_load_dwordx4 v[78:81], v[56:57], off offset:768
	global_load_dwordx4 v[38:41], v[56:57], off offset:2304
	v_addc_co_u32_e32 v27, vcc, 0, v57, vcc
	global_load_dwordx4 v[74:77], v[26:27], off offset:768
	global_load_dwordx4 v[34:37], v[26:27], off offset:2304
	v_add_co_u32_e32 v26, vcc, 0x2000, v56
	s_and_b32 s7, s2, 0x7e0
	s_nop 0
	v_addc_co_u32_e32 v27, vcc, 0, v57, vcc
	global_load_dwordx4 v[70:73], v[26:27], off offset:768
	global_load_dwordx4 v[30:33], v[26:27], off offset:2304
	v_add_co_u32_e32 v26, vcc, 0x3000, v56
	v_lshlrev_b32_e32 v86, 3, v42
	s_nop 0
	v_addc_co_u32_e32 v27, vcc, 0, v57, vcc
	global_load_dwordx4 v[58:61], v[26:27], off offset:768
	s_nop 0
	global_load_dwordx4 v[26:29], v[26:27], off offset:2304
	v_add_u32_e32 v63, s7, v150
	v_cmp_lt_i32_e32 vcc, 1, v63
	v_mov_b32_e32 v46, 0
	v_lshlrev_b32_e32 v84, 1, v86
	v_mov_b32_e32 v42, 0
	v_mov_b32_e32 v43, 0
	v_mov_b32_e32 v44, 0
	v_mov_b32_e32 v45, 0
	s_and_saveexec_b64 s[2:3], vcc
	s_cbranch_execz .LBB0_823
	v_mov_b32_e32 v85, v155
	v_lshl_add_u64 v[42:43], v[82:83], 0, v[84:85]
	v_add_co_u32_e32 v42, vcc, 0xfffff000, v42
	s_nop 1
	v_addc_co_u32_e32 v43, vcc, -1, v43, vcc
	global_load_dwordx4 v[42:45], v[42:43], off offset:-2560
